# up-phase last round units reassigned to the less loaded workgroups (balances UQ/UKV work per CU)
# speedup vs baseline: 1.0183x; 1.0043x over previous
;     DI bool next(int i, Unit& u) const {
;     ...
;         } else if (mode == M_UP) {
;             const long L = (long)i * G + c; if (L >= nM * 7) return false;
;             if (L < nM * 3) { tile_map((int)L, nM, 3, u.pm, u.pn); u.lda = 1536; u.ldb = 1536; u.nt = 12; u.kind = K_UQ;
;                 u.A = ws + WS_QLAT + (size_t)u.pm * BM * 1536; u.B = ws + W_UQ + (size_t)u.pn * BM * 1536; }
;             else { tile_map((int)L - nM * 3, nM, 4, u.pm, u.pn); u.lda = 512; u.ldb = 512; u.nt = 4; u.kind = K_UKV;
;                 u.A = ws + WS_CKV + (size_t)u.pm * BM * 512; u.B = ws + W_UKV + (size_t)u.pn * BM * 512; }
;             return true;
.LBB0_308:
	s_andn2_b64 vcc, exec, s[76:77]
	s_cbranch_vccnz .LBB0_327
	v_readlane_b32 s28, v254, 20
	s_mov_b64 s[76:77], -1
	s_cmp_gt_i32 s15, 0
	s_mul_i32 s43, s73, s28
	s_mul_hi_u32 s71, s73, s62
	s_mul_i32 s80, s73, s62
	s_cbranch_scc0 .LBB0_317
	s_add_i32 s28, s71, s43
	s_add_u32 s78, s80, s65
	s_addc_u32 s79, s28, s27
	s_cmp_eq_u32 s73, 3
	s_cbranch_scc0 .Lup_keep
	s_cmpk_eq_u32 s62, 0x100
	s_cbranch_scc0 .Lup_keep
	s_xor_b32 s28, s65, 0x80
	s_add_u32 s78, s28, 0x300
	s_mov_b32 s79, 0
.Lup_keep:
	v_mov_b64_e32 v[2:3], 0x37f
	v_cmp_gt_i64_e32 vcc, s[78:79], v[2:3]
	s_mov_b64 s[76:77], 0
	s_and_b64 vcc, exec, vcc
	s_mov_b64 s[28:29], 0
	s_mov_b64 s[44:45], s[58:59]
	s_mov_b64 s[50:51], s[74:75]
	s_mov_b32 s47, s39
	s_mov_b32 s70, s68
	s_mov_b32 s57, s63
	s_mov_b32 s49, s23
	s_mov_b32 s48, s56
	s_mov_b32 s46, s22
	s_cbranch_vccnz .LBB0_317
	v_mov_b64_e32 v[2:3], 0x17f
	v_cmp_gt_i64_e32 vcc, s[78:79], v[2:3]
	s_mov_b64 s[28:29], -1
	s_and_b64 vcc, exec, vcc
	s_cbranch_vccz .LBB0_313
	s_add_i32 s28, s78, 0xfe80
	s_lshl_b32 s29, s78, 6
	s_bfe_u32 s44, s28, 0x80008
	s_and_b32 s29, s29, 0x1c0
	s_lshl_b32 s44, s44, 5
	s_add_i32 s44, s44, s29
	s_lshr_b32 s29, s44, 2
	s_bfe_u32 s44, s28, 0x30003
	s_or_b32 s48, s29, s44
	s_ashr_i32 s49, s48, 31
	s_bfe_u32 s46, s28, 0x20006
	s_lshl_b64 s[28:29], s[48:49], 17
	v_readlane_b32 s40, v252, 25
	s_add_u32 s44, s40, s28
	v_readlane_b32 s28, v252, 26
	s_addc_u32 s45, s28, s29
	s_lshl_b32 s28, s46, 17
	v_readlane_b32 s29, v252, 27
	s_add_u32 s50, s29, s28
	v_readlane_b32 s28, v252, 28
	s_addc_u32 s51, s28, 0
	s_mov_b64 s[28:29], 0
